# K-tile LDS XOR swizzle widened to 16 chunks (row&15) to cut bank conflicts on QK K-fragment reads
# speedup vs baseline: 1.0078x; 1.0078x over previous
; DI void attn_stage(const bf16_t* kbase, const bf16_t* vbase, unsigned koff, unsigned voff, LAS unsigned char* ldsbuf, int wid) {
; #pragma unroll
;     for (int i = 0; i < 2; ++i) {
;         const char* src = (const char*)kbase + (size_t)(i * 128) * 2;
;         __builtin_amdgcn_global_load_lds((const unsigned*)(src + koff), (LAS unsigned*)(ldsbuf + (wid + 8 * i) * 1024), 16, 0, 0);
;     }
; #pragma unroll
;     for (int i = 0; i < 2; ++i) {
;         const char* src = (const char*)vbase + (size_t)(16 * i * 2048) * 2;
; DI void phase_attn(int wid0, const Params& p, int L, unsigned char* lds, bool dry) {
;     ...
;         { const int row = 4 * wid + (lane >> 4), gsrc = (lane & 15) ^ (row & 7); koff = (unsigned)(row * 2048 + 8 * gsrc) * 2u;
;           const int w5 = (lane & 31) >> 2, kl = (w5 & 3) + 8 * (w5 >> 2) + 4 * (wid >> 2), col = ((2 * wid + (lane >> 5)) & 7) * 32 + (lane & 3) * 8; voff = (unsigned)(kl * 2048 + col) * 2u; }
;         if (G == 256) {
;             if (ui < 8) { const int bh = 8 * ui + (blk & 7), j = blk >> 3; qb = (ui & 1) ? j : 31 - j; b = bh >> 3; hh = bh & 7; }
;             else if (ui == 8 && blk < 8) { meta = true; hh = blk; b = 0; qb = 0; }
;             else break;
;         } else {
;             const int u = blk + ui * G;
;             if (u < 2048) { const int bh = u & 63; qb = 31 - (u >> 6); b = bh >> 3; hh = bh & 7; }
;             else if (u < 2056) { meta = true; hh = u - 2048; b = 0; qb = 0; }
;             else break;
;         }
;         const int qrow0 = meta ? MREG : b * 4096 + 128 * qb, qpos0 = meta ? 0 : 16 + 128 * qb, ntiles = meta ? 1 : 1 + 4 * (qb + 1);
;         if (tid < 130) tab[tid] = (tid < 129) ? biasT[hh * 129 + tid] : -__builtin_inff();
;         int myrow = qrow0 + 32 * rg + r32; if (meta && myrow > MREG + 63) myrow = MREG + 63;
;         const bf16_t* qp = qbuf + (size_t)myrow * 2048 + hh * 256 + psub * 128 + hi * 8;
;         unsigned char* qlds = lds + wid * 8192 + lane * 16;
; #pragma unroll
;         for (int d0 = 0; d0 < 8; ++d0) *(bf16x8*)(qlds + d0 * 1024) = *(const bf16x8*)(qp + d0 * 16);
;         const int wq0 = qpos0 + 32 * rg, qpos = wq0 + r32;
;         const float bfar = biasT[hh * 129 + 128];
;         const bf16_t* kh_ = kbuf + hh * 256; const bf16_t* vh_ = vbuf + hh * 256;
;         attn_stage(kh_ + (size_t)MREG * 2048, vh_ + (size_t)MREG * 2048, koff, voff, ldsl + 65536, wid);
.LBB0_97:
	s_or_b64 exec, exec, s[10:11]
	s_lshl_b32 s40, s73, 12
	s_lshl_b32 s10, s75, 7
	s_add_i32 s9, s40, s10
	s_and_b64 s[6:7], s[76:77], exec
	s_cselect_b32 s71, 0x8000, s9
	s_lshl_b32 s6, s75, 2
	s_add_i32 s9, s6, 5
	s_and_b64 s[6:7], s[76:77], exec
	v_ashrrev_i32_e32 v0, 4, v4
	v_readlane_b32 s7, v245, 61
	v_and_b32_e32 v2, 15, v4
	v_lshrrev_b32_e32 v3, 1, v4
	v_add_u32_e32 v0, s7, v0
	v_bitop3_b32 v2, v0, v2, 15 bitop3:0x6c
	v_lshlrev_b32_e32 v0, 12, v0
	v_lshl_or_b32 v0, v2, 4, v0
	v_lshrrev_b32_e32 v2, 2, v4
	v_and_b32_e32 v3, 8, v3
	v_readlane_b32 s7, v245, 63
	v_and_or_b32 v2, v2, 3, v3
	v_lshlrev_b32_e32 v8, 3, v4
	v_add_u32_e32 v3, s7, v4
	v_readlane_b32 s7, v244, 1
	v_and_b32_e32 v7, 31, v4
	v_and_b32_e32 v3, 0xe0, v3
	v_and_b32_e32 v5, 24, v8
	v_lshl_add_u32 v2, v2, 11, s7
	v_or3_b32 v2, v2, v3, v5
	v_or_b32_e32 v3, s41, v7
	v_or_b32_e32 v3, s71, v3
	v_min_i32_e32 v9, 0x803f, v3
	v_cndmask_b32_e64 v10, v3, v9, s[76:77]
	s_cselect_b32 s6, 1, s9
	v_ashrrev_i32_e32 v11, 31, v10
	s_lshl_b32 s12, s49, 8
	v_lshlrev_b64 v[10:11], 12, v[10:11]
	s_ashr_i32 s13, s12, 31
	v_ashrrev_i32_e32 v6, 5, v4
	v_lshl_add_u64 v[10:11], s[0:1], 0, v[10:11]
	s_lshl_b64 s[78:79], s[12:13], 1
	v_readlane_b32 s12, v244, 5
	v_lshl_add_u64 v[10:11], v[10:11], 0, s[78:79]
	v_readlane_b32 s13, v244, 6
	v_lshlrev_b32_e32 v12, 3, v6
	v_ashrrev_i32_e32 v13, 31, v12
	v_lshl_add_u64 v[10:11], s[12:13], 1, v[10:11]
	v_lshl_add_u64 v[14:15], v[12:13], 1, v[10:11]
	global_load_dwordx4 v[10:13], v[14:15], off
	s_ashr_i32 s9, s8, 31
	s_lshl_b64 s[8:9], s[8:9], 2
	v_readlane_b32 s12, v245, 40
	v_lshlrev_b32_e32 v9, 4, v4
	v_readlane_b32 s7, v244, 7
	v_readlane_b32 s13, v245, 41
	s_add_u32 s8, s12, s8
	v_add_u32_e32 v131, s7, v9
	s_addc_u32 s9, s13, s9
	global_load_dword v176, v1, s[8:9] offset:512
	s_add_u32 s12, s28, s78
	s_addc_u32 s13, s29, s79
	v_readlane_b32 s8, v245, 38
	v_readlane_b32 s9, v245, 39
	s_add_u32 s8, s8, s78
	v_readlane_b32 s7, v244, 9
	s_addc_u32 s9, s9, s79
	v_lshl_add_u64 v[178:179], s[12:13], 0, v[0:1]
	s_mov_b64 s[14:15], 0x8000000
	s_add_i32 s7, s7, 0
	v_lshlrev_b32_e32 v2, 1, v2
	s_add_i32 m0, s7, 0x10000
	s_mov_b64 s[12:13], 0x8000100
	v_mov_b32_e32 v3, v1
	v_lshl_add_u64 v[180:181], s[8:9], 0, v[2:3]
	v_lshl_add_u64 v[2:3], v[180:181], 0, s[14:15]
	s_mov_b64 s[8:9], 0x8010000
	s_waitcnt vmcnt(1)
	ds_write_b128 v131, v[10:13]
	global_load_dwordx4 v[10:13], v[14:15], off offset:32
	s_waitcnt vmcnt(0)
	ds_write_b128 v131, v[10:13] offset:1024
	global_load_dwordx4 v[10:13], v[14:15], off offset:64
	s_waitcnt vmcnt(0)
	ds_write_b128 v131, v[10:13] offset:2048
	global_load_dwordx4 v[10:13], v[14:15], off offset:96
	s_waitcnt vmcnt(0)
	ds_write_b128 v131, v[10:13] offset:3072
	global_load_dwordx4 v[10:13], v[14:15], off offset:128
	s_waitcnt vmcnt(0)
	ds_write_b128 v131, v[10:13] offset:4096
	global_load_dwordx4 v[10:13], v[14:15], off offset:160
	s_waitcnt vmcnt(0)
	ds_write_b128 v131, v[10:13] offset:5120
	global_load_dwordx4 v[10:13], v[14:15], off offset:192
	s_waitcnt vmcnt(0)
	ds_write_b128 v131, v[10:13] offset:6144
	global_load_dwordx4 v[10:13], v[14:15], off offset:224
	s_waitcnt vmcnt(0)
	ds_write_b128 v131, v[10:13] offset:7168
	v_lshl_add_u64 v[10:11], v[178:179], 0, s[14:15]
	global_load_lds_dwordx4 v[10:11], off
	v_lshl_add_u64 v[10:11], v[178:179], 0, s[12:13]
	s_add_i32 m0, s7, 0x12000
	s_nop 0
	global_load_lds_dwordx4 v[10:11], off
	s_add_i32 m0, s7, 0x14000
	s_nop 0
	global_load_lds_dwordx4 v[2:3], off
	v_lshl_add_u64 v[2:3], v[180:181], 0, s[8:9]
	s_add_i32 m0, s7, 0x16000
	s_mov_b32 s7, 0
	global_load_lds_dwordx4 v[2:3], off
	s_cmp_lt_i32 s6, 1
	s_cbranch_scc1 .LBB0_114
; DI void phase_attn(int wid0, const Params& p, int L, unsigned char* lds, bool dry) {
;     ...
; #pragma unroll
;             for (int r = 0; r < 16; ++r) o[d][r] = 0.f;
;         float m_reg = -1e30f, l_reg = 0.f;
;         for (int t = 0; t < ntiles; ++t) {
;             asm volatile("s_waitcnt vmcnt(0) lgkmcnt(0)" ::: "memory"); __builtin_amdgcn_s_barrier(); asm volatile("" ::: "memory");
;             if (t + 1 < ntiles) attn_stage(kh_ + (size_t)(b * 4096 + 32 * t) * 2048, vh_ + (size_t)(b * 4096 + 32 * t) * 2048, koff, voff, ldsl + 65536 + ((t + 1) & 1) * 32768, wid);
;             const int kpos0 = (t == 0) ? 0 : 16 + 32 * (t - 1);
;             if (kpos0 <= wq0 + 31) {
;                 const unsigned char* Ks = lds + 65536 + (t & 1) * 32768 + psub * 8192;
;                 f32x16 p0, p0b;
; #pragma unroll
;                 for (int r = 0; r < 16; ++r) { p0[r] = 0.f; p0b[r] = 0.f; }
;                 int swz = (r32 & 6) << 4, kro = r32 * 256 + ((hi ^ (r32 & 1)) << 4); asm volatile("" : "+v"(swz), "+v"(kro));
	s_or_b32 s10, s10, 16
	v_lshlrev_b32_e32 v0, 8, v7
	v_bitop3_b32 v2, v6, v4, 1 bitop3:0x78
	s_and_b64 s[8:9], s[76:77], exec
	v_lshl_add_u32 v193, v2, 4, v0
	v_lshlrev_b32_e32 v2, 1, v4
	s_cselect_b32 s39, 0, s10
	v_and_b32_e32 v0, 0xc0, v9
	v_and_b32_e32 v2, 32, v2
	v_readlane_b32 s48, v244, 17
	s_or_b32 s8, s39, s41
	v_and_b32_e32 v3, 0x100, v8
	v_add3_u32 v0, s48, v0, v2
	v_mov_b32_e32 v14, v1
	v_mov_b32_e32 v15, v1
	s_add_i32 s38, s8, 31
	v_and_b32_e32 v192, 0xe0, v9
	v_lshlrev_b32_e32 v194, 2, v6
	v_add_u32_e32 v195, s8, v7
	v_cmp_gt_u32_e64 s[8:9], 32, v4
	v_lshl_add_u32 v196, v7, 2, s2
	v_lshlrev_b32_e32 v16, 4, v6
	v_cmp_gt_i32_e64 s[10:11], 4, v6
	v_cmp_gt_i32_e64 s[18:19], 2, v6
	v_cmp_gt_i32_e64 s[20:21], 0, v6
	v_cmp_gt_i32_e64 s[22:23], -2, v6
	v_add3_u32 v212, v0, v3, v5
	v_mov_b32_e32 v0, v1
	v_mov_b32_e32 v2, v1
	v_mov_b32_e32 v3, v1
	v_mov_b32_e32 v4, v1
	v_mov_b32_e32 v5, v1
	v_mov_b32_e32 v6, v1
	v_mov_b32_e32 v7, v1
	v_mov_b32_e32 v8, v1
	v_mov_b32_e32 v9, v1
	v_mov_b32_e32 v10, v1
	v_mov_b32_e32 v11, v1
	v_mov_b32_e32 v12, v1
	v_mov_b32_e32 v13, v1
	v_mov_b64_e32 v[128:129], v[14:15]
	v_mov_b64_e32 v[112:113], v[14:15]
	v_mov_b64_e32 v[96:97], v[14:15]
	v_mov_b64_e32 v[80:81], v[14:15]
	v_mov_b64_e32 v[64:65], v[14:15]
	v_mov_b64_e32 v[48:49], v[14:15]
	v_mov_b64_e32 v[32:33], v[14:15]
	v_or_b32_e32 v197, 1, v194
	v_or_b32_e32 v198, 2, v194
	v_or_b32_e32 v199, 3, v194
	v_readlane_b32 s48, v244, 19
	v_add_u32_e32 v214, s2, v16
	v_mov_b64_e32 v[126:127], v[12:13]
	v_mov_b64_e32 v[124:125], v[10:11]
	v_mov_b64_e32 v[122:123], v[8:9]
	v_mov_b64_e32 v[120:121], v[6:7]
	v_mov_b64_e32 v[118:119], v[4:5]
	v_mov_b64_e32 v[116:117], v[2:3]
	v_mov_b64_e32 v[114:115], v[0:1]
	v_mov_b64_e32 v[110:111], v[12:13]
	v_mov_b64_e32 v[108:109], v[10:11]
	v_mov_b64_e32 v[106:107], v[8:9]
	v_mov_b64_e32 v[104:105], v[6:7]
	v_mov_b64_e32 v[102:103], v[4:5]
	v_mov_b64_e32 v[100:101], v[2:3]
	v_mov_b64_e32 v[98:99], v[0:1]
	v_mov_b64_e32 v[94:95], v[12:13]
	v_mov_b64_e32 v[92:93], v[10:11]
	v_mov_b64_e32 v[90:91], v[8:9]
	v_mov_b64_e32 v[88:89], v[6:7]
	v_mov_b64_e32 v[86:87], v[4:5]
	v_mov_b64_e32 v[84:85], v[2:3]
	v_mov_b64_e32 v[82:83], v[0:1]
	v_mov_b64_e32 v[78:79], v[12:13]
	v_mov_b64_e32 v[76:77], v[10:11]
	v_mov_b64_e32 v[74:75], v[8:9]
	v_mov_b64_e32 v[72:73], v[6:7]
	v_mov_b64_e32 v[70:71], v[4:5]
	v_mov_b64_e32 v[68:69], v[2:3]
	v_mov_b64_e32 v[66:67], v[0:1]
	v_mov_b64_e32 v[62:63], v[12:13]
	v_mov_b64_e32 v[60:61], v[10:11]
	v_mov_b64_e32 v[58:59], v[8:9]
	v_mov_b64_e32 v[56:57], v[6:7]
	v_mov_b64_e32 v[54:55], v[4:5]
	v_mov_b64_e32 v[52:53], v[2:3]
	v_mov_b64_e32 v[50:51], v[0:1]
	v_mov_b64_e32 v[46:47], v[12:13]
	v_mov_b64_e32 v[44:45], v[10:11]
	v_mov_b64_e32 v[42:43], v[8:9]
	v_mov_b64_e32 v[40:41], v[6:7]
	v_mov_b64_e32 v[38:39], v[4:5]
	v_mov_b64_e32 v[36:37], v[2:3]
	v_mov_b64_e32 v[34:35], v[0:1]
	v_mov_b64_e32 v[30:31], v[12:13]
	v_mov_b64_e32 v[28:29], v[10:11]
	v_mov_b64_e32 v[26:27], v[8:9]
	v_mov_b64_e32 v[24:25], v[6:7]
	v_mov_b64_e32 v[22:23], v[4:5]
	v_mov_b64_e32 v[20:21], v[2:3]
	v_mov_b64_e32 v[18:19], v[0:1]
	v_mov_b64_e32 v[16:17], v[14:15]
	v_cmp_gt_i32_e64 s[12:13], 16, v197
	v_cmp_gt_i32_e64 s[14:15], 16, v198
	v_cmp_gt_i32_e64 s[16:17], 16, v199
	v_add_u32_e32 v200, -8, v195
	v_add_u32_e32 v201, -9, v195
	v_add_u32_e32 v202, -10, v195
	v_add_u32_e32 v203, -11, v195
	v_add_u32_e32 v204, -16, v195
	v_subrev_u32_e32 v205, 17, v195
	v_subrev_u32_e32 v206, 18, v195
	v_subrev_u32_e32 v207, 19, v195
	v_subrev_u32_e32 v208, 24, v195
	v_subrev_u32_e32 v209, 25, v195
	v_subrev_u32_e32 v210, 26, v195
	v_subrev_u32_e32 v211, 27, v195
	v_mov_b32_e32 v182, v176
	v_mov_b32_e32 v183, v176
	s_add_i32 s39, s48, s39
	v_mov_b32_e32 v130, 0
	v_mov_b32_e32 v213, 0xf149f2ca
	s_mov_b32 s66, 0
	v_mov_b64_e32 v[14:15], v[12:13]
	v_mov_b64_e32 v[12:13], v[10:11]
	v_mov_b64_e32 v[10:11], v[8:9]
	v_mov_b64_e32 v[8:9], v[6:7]
	v_mov_b64_e32 v[6:7], v[4:5]
	v_mov_b64_e32 v[4:5], v[2:3]
	v_mov_b64_e32 v[2:3], v[0:1]
	s_mov_b32 s69, 0
